# best_v5 + CV2: phase-8 o_w_in conversion loop rewritten with two tiles of global loads in flight (alternating register sets)
# speedup vs baseline: 1.0068x; 1.0068x over previous
.LBB0_1110:
	s_andn2_b64 vcc, exec, s[6:7]
	s_cbranch_vccnz .LBB0_1117
	s_andn2_b64 vcc, exec, s[4:5]
	s_cbranch_vccnz .LBB0_1117
	s_cmpk_gt_i32 s58, 0x7ff
	s_waitcnt vmcnt(0)
	s_barrier
	s_cbranch_scc1 .LBB0_1117
	s_ashr_i32 s0, s58, 31
	s_lshr_b32 s0, s0, 28
	s_add_i32 s0, s58, s0
	s_load_dwordx2 s[4:5], s[60:61], 0xd8
	s_ashr_i32 s1, s0, 4
	s_and_b32 s2, s0, 0x3fffff0
	s_sub_i32 s2, s58, s2
	v_lshl_or_b32 v2, s1, 6, v202
	v_bfe_u32 v1, v0, 4, 1
	v_lshrrev_b32_e32 v26, 6, v0
	v_and_or_b32 v3, s1, 2, v1
	s_andn2_b32 s0, s0, 63
	v_lshrrev_b32_e32 v2, 1, v2
	v_lshl_or_b32 v4, s2, 6, v26
	v_lshl_add_u32 v3, v3, 11, s0
	v_and_b32_e32 v2, 48, v2
	v_ashrrev_i32_e32 v5, 31, v4
	v_or3_b32 v2, v3, v2, v201
	v_lshlrev_b64 v[4:5], 15, v[4:5]
	s_waitcnt lgkmcnt(0)
	v_lshl_add_u64 v[4:5], s[4:5], 0, v[4:5]
	v_ashrrev_i32_e32 v3, 31, v2
	v_lshl_add_u64 v[2:3], v[2:3], 2, v[4:5]
	s_mov_b32 s0, 0x40000
	v_add_co_u32_e32 v4, vcc, s0, v2
	s_mov_b32 s1, 0x80000
	s_nop 0
	v_addc_co_u32_e32 v5, vcc, 0, v3, vcc
	v_add_co_u32_e32 v6, vcc, s1, v2
	s_mov_b32 s2, 0xc0000
	s_nop 0
	v_addc_co_u32_e32 v7, vcc, 0, v3, vcc
	v_add_co_u32_e32 v8, vcc, s2, v2
	s_mov_b32 s3, 0x100000
	s_nop 0
	v_addc_co_u32_e32 v9, vcc, 0, v3, vcc
	v_add_co_u32_e32 v10, vcc, s3, v2
	s_mov_b32 s3, 0x140000
	s_nop 0
	v_addc_co_u32_e32 v11, vcc, 0, v3, vcc
	v_add_co_u32_e32 v12, vcc, s3, v2
	s_mov_b32 s3, 0x180000
	s_nop 0
	v_addc_co_u32_e32 v13, vcc, 0, v3, vcc
	v_add_co_u32_e32 v14, vcc, s3, v2
	s_mov_b32 s3, 0x1c0000
	s_nop 0
	v_addc_co_u32_e32 v15, vcc, 0, v3, vcc
	v_add_co_u32_e32 v16, vcc, s3, v2
	s_mov_b64 s[6:7], 0x800000
	s_nop 0
	v_addc_co_u32_e32 v17, vcc, 0, v3, vcc
	global_load_dword v18, v[2:3], off
	global_load_dword v19, v[4:5], off
	global_load_dword v20, v[6:7], off
	global_load_dword v21, v[8:9], off
	global_load_dword v22, v[10:11], off
	global_load_dword v23, v[12:13], off
	global_load_dword v24, v[14:15], off
	global_load_dword v25, v[16:17], off
	v_lshlrev_b32_e32 v4, 3, v0
	v_and_b32_e32 v4, 56, v4
	v_and_b32_e32 v6, 63, v0
	v_mul_u32_u24_e32 v5, 0x104, v4
	v_lshlrev_b32_e32 v7, 2, v200
	v_lshl_add_u32 v9, v6, 2, 0
	v_add3_u32 v7, 0, v5, v7
	v_mov_b32_e32 v5, 0
	v_mul_u32_u24_e32 v10, 0x104, v26
	s_lshl_b32 s8, s73, 6
	v_lshl_add_u64 v[2:3], v[166:167], 0, s[6:7]
	s_lshl_b32 s3, s58, 6
	v_or_b32_e32 v8, s8, v26
	v_add_u32_e32 v9, v9, v10
	s_movk_i32 s9, 0x7fff
	s_mov_b32 s10, 0xffff0000
	v_lshlrev_b32_e32 v4, 1, v4
	s_mov_b32 s12, s58
	v_mov_b32_e32 v10, v5
	v_mov_b32_e32 v11, v5
	v_mov_b32_e32 v12, v5
	v_mov_b32_e32 v13, v5
	v_mov_b32_e32 v14, v5
	v_mov_b32_e32 v15, v5
	v_mov_b32_e32 v16, v5
	v_mov_b32_e32 v17, v5
	s_add_i32 s26, s12, s73
	s_cmpk_gt_i32 s26, 0x7ff
	s_cbranch_scc1 .Lcv2_A
	s_ashr_i32 s13, s26, 31
	s_lshr_b32 s13, s13, 28
	s_add_i32 s13, s26, s13
	s_ashr_i32 s16, s13, 4
	v_lshl_or_b32 v60, s16, 6, v6
	v_and_or_b32 v61, s16, 2, v1
	s_andn2_b32 s13, s13, 63
	v_lshrrev_b32_e32 v60, 1, v60
	v_lshl_add_u32 v61, v61, 11, s13
	v_and_b32_e32 v60, 48, v60
	v_or3_b32 v60, v61, v60, v201
	v_add_u32_e32 v61, s3, v8
	s_lshl_b32 s13, s16, 10
	v_subrev_u32_e32 v62, s13, v61
	v_ashrrev_i32_e32 v63, 31, v62
	v_lshlrev_b64 v[62:63], 15, v[62:63]
	v_lshl_add_u64 v[62:63], s[4:5], 0, v[62:63]
	v_ashrrev_i32_e32 v61, 31, v60
	v_lshl_add_u64 v[64:65], v[60:61], 2, v[62:63]
	v_add_co_u32_e32 v66, vcc, s0, v64
	s_nop 1
	v_addc_co_u32_e32 v67, vcc, 0, v65, vcc
	v_add_co_u32_e32 v68, vcc, s1, v64
	s_nop 1
	v_addc_co_u32_e32 v69, vcc, 0, v65, vcc
	v_add_co_u32_e32 v70, vcc, s2, v64
	s_nop 1
	v_addc_co_u32_e32 v71, vcc, 0, v65, vcc
	v_add_co_u32_e32 v72, vcc, 0x100000, v64
	s_nop 1
	v_addc_co_u32_e32 v73, vcc, 0, v65, vcc
	v_add_co_u32_e32 v74, vcc, 0x140000, v64
	s_nop 1
	v_addc_co_u32_e32 v75, vcc, 0, v65, vcc
	v_add_co_u32_e32 v76, vcc, 0x180000, v64
	s_nop 1
	v_addc_co_u32_e32 v77, vcc, 0, v65, vcc
	v_add_co_u32_e32 v78, vcc, 0x1c0000, v64
	s_nop 1
	v_addc_co_u32_e32 v79, vcc, 0, v65, vcc
	global_load_dword v10, v[64:65], off
	global_load_dword v11, v[66:67], off
	global_load_dword v12, v[68:69], off
	global_load_dword v13, v[70:71], off
	global_load_dword v14, v[72:73], off
	global_load_dword v15, v[74:75], off
	global_load_dword v16, v[76:77], off
	global_load_dword v17, v[78:79], off
.Lcv2_A:
	s_add_i32 s26, s12, s73
	s_add_i32 s27, s26, s73
	s_cmpk_gt_i32 s26, 0x7ff
	s_cbranch_scc0 .Lcv2_A_more
	s_waitcnt vmcnt(0)
.Lcv2_A_more:
	s_waitcnt vmcnt(8)
	ds_write_b32 v9, v18 offset:32768
	ds_write_b32 v9, v19 offset:34848
	ds_write_b32 v9, v20 offset:36928
	ds_write_b32 v9, v21 offset:39008
	ds_write_b32 v9, v22 offset:41088
	ds_write_b32 v9, v23 offset:43168
	ds_write_b32 v9, v24 offset:45248
	ds_write_b32 v9, v25 offset:47328
	s_cmpk_gt_i32 s27, 0x7ff
	s_cbranch_scc1 .Lcv2_A_noload
	s_add_i32 s28, s3, s8
	s_ashr_i32 s13, s27, 31
	s_lshr_b32 s13, s13, 28
	s_add_i32 s13, s27, s13
	s_ashr_i32 s16, s13, 4
	v_lshl_or_b32 v60, s16, 6, v6
	v_and_or_b32 v61, s16, 2, v1
	s_andn2_b32 s13, s13, 63
	v_lshrrev_b32_e32 v60, 1, v60
	v_lshl_add_u32 v61, v61, 11, s13
	v_and_b32_e32 v60, 48, v60
	v_or3_b32 v60, v61, v60, v201
	v_add_u32_e32 v61, s28, v8
	s_lshl_b32 s13, s16, 10
	v_subrev_u32_e32 v62, s13, v61
	v_ashrrev_i32_e32 v63, 31, v62
	v_lshlrev_b64 v[62:63], 15, v[62:63]
	v_lshl_add_u64 v[62:63], s[4:5], 0, v[62:63]
	v_ashrrev_i32_e32 v61, 31, v60
	v_lshl_add_u64 v[64:65], v[60:61], 2, v[62:63]
	v_add_co_u32_e32 v66, vcc, s0, v64
	s_nop 1
	v_addc_co_u32_e32 v67, vcc, 0, v65, vcc
	v_add_co_u32_e32 v68, vcc, s1, v64
	s_nop 1
	v_addc_co_u32_e32 v69, vcc, 0, v65, vcc
	v_add_co_u32_e32 v70, vcc, s2, v64
	s_nop 1
	v_addc_co_u32_e32 v71, vcc, 0, v65, vcc
	v_add_co_u32_e32 v72, vcc, 0x100000, v64
	s_nop 1
	v_addc_co_u32_e32 v73, vcc, 0, v65, vcc
	v_add_co_u32_e32 v74, vcc, 0x140000, v64
	s_nop 1
	v_addc_co_u32_e32 v75, vcc, 0, v65, vcc
	v_add_co_u32_e32 v76, vcc, 0x180000, v64
	s_nop 1
	v_addc_co_u32_e32 v77, vcc, 0, v65, vcc
	v_add_co_u32_e32 v78, vcc, 0x1c0000, v64
	s_nop 1
	v_addc_co_u32_e32 v79, vcc, 0, v65, vcc
	global_load_dword v18, v[64:65], off
	global_load_dword v19, v[66:67], off
	global_load_dword v20, v[68:69], off
	global_load_dword v21, v[70:71], off
	global_load_dword v22, v[72:73], off
	global_load_dword v23, v[74:75], off
	global_load_dword v24, v[76:77], off
	global_load_dword v25, v[78:79], off
.Lcv2_A_noload:
	v_add_u32_e32 v88, 0x8000, v7
	s_waitcnt lgkmcnt(0)
	s_barrier
	ds_read2_b32 v[80:81], v88 offset1:65
	ds_read2_b32 v[82:83], v88 offset0:130 offset1:195
	v_add_u32_e32 v88, 0x8400, v7
	ds_read2_b32 v[84:85], v88 offset0:4 offset1:69
	ds_read2_b32 v[86:87], v88 offset0:134 offset1:199
	s_ashr_i32 s13, s12, 31
	s_lshr_b32 s13, s13, 28
	s_add_i32 s29, s12, s13
	s_ashr_i32 s13, s29, 4
	v_lshl_or_b32 v90, s13, 6, v200
	s_lshl_b32 s29, s13, 10
	v_ashrrev_i32_e32 v91, 31, v90
	s_sub_i32 s30, s3, s29
	v_lshlrev_b64 v[90:91], 11, v[90:91]
	v_lshl_add_u64 v[90:91], v[2:3], 0, v[90:91]
	s_ashr_i32 s31, s30, 31
	v_lshl_add_u64 v[90:91], s[30:31], 1, v[90:91]
	v_lshl_add_u64 v[90:91], v[90:91], 0, v[4:5]
	s_waitcnt lgkmcnt(3)
	v_cvt_pk_bf16_f32 v92, v80, v81
	s_waitcnt lgkmcnt(2)
	v_cvt_pk_bf16_f32 v93, v82, v83
	s_waitcnt lgkmcnt(1)
	v_cvt_pk_bf16_f32 v94, v84, v85
	s_waitcnt lgkmcnt(0)
	v_cvt_pk_bf16_f32 v95, v86, v87
	global_store_dwordx4 v[90:91], v[92:95], off
	s_add_i32 s3, s3, s8
	s_mov_b32 s12, s26
	s_barrier
	s_cmpk_gt_i32 s12, 0x7ff
	s_cbranch_scc1 .LBB0_1117

.Lcv2_B_more:
	s_waitcnt vmcnt(8)
	ds_write_b32 v9, v10 offset:32768
	ds_write_b32 v9, v11 offset:34848
	ds_write_b32 v9, v12 offset:36928
	ds_write_b32 v9, v13 offset:39008
	ds_write_b32 v9, v14 offset:41088
	ds_write_b32 v9, v15 offset:43168
	ds_write_b32 v9, v16 offset:45248
	ds_write_b32 v9, v17 offset:47328
	s_cmpk_gt_i32 s27, 0x7ff
	s_cbranch_scc1 .Lcv2_B_noload
	s_add_i32 s28, s3, s8
	s_ashr_i32 s13, s27, 31
	s_lshr_b32 s13, s13, 28
	s_add_i32 s13, s27, s13
	s_ashr_i32 s16, s13, 4
	v_lshl_or_b32 v60, s16, 6, v6
	v_and_or_b32 v61, s16, 2, v1
	s_andn2_b32 s13, s13, 63
	v_lshrrev_b32_e32 v60, 1, v60
	v_lshl_add_u32 v61, v61, 11, s13
	v_and_b32_e32 v60, 48, v60
	v_or3_b32 v60, v61, v60, v201
	v_add_u32_e32 v61, s28, v8
	s_lshl_b32 s13, s16, 10
	v_subrev_u32_e32 v62, s13, v61
	v_ashrrev_i32_e32 v63, 31, v62
	v_lshlrev_b64 v[62:63], 15, v[62:63]
	v_lshl_add_u64 v[62:63], s[4:5], 0, v[62:63]
	v_ashrrev_i32_e32 v61, 31, v60
	v_lshl_add_u64 v[64:65], v[60:61], 2, v[62:63]
	v_add_co_u32_e32 v66, vcc, s0, v64
	s_nop 1
	v_addc_co_u32_e32 v67, vcc, 0, v65, vcc
	v_add_co_u32_e32 v68, vcc, s1, v64
	s_nop 1
	v_addc_co_u32_e32 v69, vcc, 0, v65, vcc
	v_add_co_u32_e32 v70, vcc, s2, v64
	s_nop 1
	v_addc_co_u32_e32 v71, vcc, 0, v65, vcc
	v_add_co_u32_e32 v72, vcc, 0x100000, v64
	s_nop 1
	v_addc_co_u32_e32 v73, vcc, 0, v65, vcc
	v_add_co_u32_e32 v74, vcc, 0x140000, v64
	s_nop 1
	v_addc_co_u32_e32 v75, vcc, 0, v65, vcc
	v_add_co_u32_e32 v76, vcc, 0x180000, v64
	s_nop 1
	v_addc_co_u32_e32 v77, vcc, 0, v65, vcc
	v_add_co_u32_e32 v78, vcc, 0x1c0000, v64
	s_nop 1
	v_addc_co_u32_e32 v79, vcc, 0, v65, vcc
	global_load_dword v10, v[64:65], off
	global_load_dword v11, v[66:67], off
	global_load_dword v12, v[68:69], off
	global_load_dword v13, v[70:71], off
	global_load_dword v14, v[72:73], off
	global_load_dword v15, v[74:75], off
	global_load_dword v16, v[76:77], off
	global_load_dword v17, v[78:79], off
.Lcv2_B_noload:
	v_add_u32_e32 v88, 0x8000, v7
	s_waitcnt lgkmcnt(0)
	s_barrier
	ds_read2_b32 v[80:81], v88 offset1:65
	ds_read2_b32 v[82:83], v88 offset0:130 offset1:195
	v_add_u32_e32 v88, 0x8400, v7
	ds_read2_b32 v[84:85], v88 offset0:4 offset1:69
	ds_read2_b32 v[86:87], v88 offset0:134 offset1:199
	s_ashr_i32 s13, s12, 31
	s_lshr_b32 s13, s13, 28
	s_add_i32 s29, s12, s13
	s_ashr_i32 s13, s29, 4
	v_lshl_or_b32 v90, s13, 6, v200
	s_lshl_b32 s29, s13, 10
	v_ashrrev_i32_e32 v91, 31, v90
	s_sub_i32 s30, s3, s29
	v_lshlrev_b64 v[90:91], 11, v[90:91]
	v_lshl_add_u64 v[90:91], v[2:3], 0, v[90:91]
	s_ashr_i32 s31, s30, 31
	v_lshl_add_u64 v[90:91], s[30:31], 1, v[90:91]
	v_lshl_add_u64 v[90:91], v[90:91], 0, v[4:5]
	s_waitcnt lgkmcnt(3)
	v_cvt_pk_bf16_f32 v92, v80, v81
	s_waitcnt lgkmcnt(2)
	v_cvt_pk_bf16_f32 v93, v82, v83
	s_waitcnt lgkmcnt(1)
	v_cvt_pk_bf16_f32 v94, v84, v85
	s_waitcnt lgkmcnt(0)
	v_cvt_pk_bf16_f32 v95, v86, v87
	global_store_dwordx4 v[90:91], v[92:95], off
	s_add_i32 s3, s3, s8
	s_mov_b32 s12, s26
	s_barrier
	s_cmpk_gt_i32 s12, 0x7ff
	s_cbranch_scc1 .LBB0_1117
	s_branch .Lcv2_A
